# P0: bf16 weight copies written with plain (cacheable) stores instead of nontemporal
# speedup vs baseline: 1.0338x; 1.0177x over previous
; __device__ __forceinline__ unsigned f2bf(float f) { unsigned u = __builtin_bit_cast(unsigned, f); return (u + 0x7fffu + ((u >> 16) & 1u)) >> 16; }
; __device__ __forceinline__ unsigned pk2(float lo, float hi) { return f2bf(lo) | (f2bf(hi) << 16); }
; __device__ __forceinline__ void p0_store(const P0Item& q, int lane, f32x4 (&v)[8]) {
;     const int nblk = q.N / 32, kb = q.item / nblk, nb = q.item % nblk, k0 = 64 * kb, n0 = 32 * nb, c = lane & 7, n4 = lane >> 3;
;     if (q.gain) { const f32x4 g0 = *(const f32x4*)(q.gain + k0 + 8 * c), g1 = *(const f32x4*)(q.gain + k0 + 8 * c + 4);
;         v[0] = v[0] * g0.x; v[1] = v[1] * g0.y; v[2] = v[2] * g0.z; v[3] = v[3] * g0.w; v[4] = v[4] * g1.x; v[5] = v[5] * g1.y; v[6] = v[6] * g1.z; v[7] = v[7] * g1.w; }
; #pragma unroll
;     for (int e = 0; e < 4; ++e) { v4u o; o.x = pk2(v[0][e], v[1][e]); o.y = pk2(v[2][e], v[3][e]); o.z = pk2(v[4][e], v[5][e]); o.w = pk2(v[6][e], v[7][e]);
;         __builtin_nontemporal_store(o, (v4u*)(q.WT + (size_t)(n0 + 4 * n4 + e) * q.K + k0 + 8 * c)); }
.LBB0_23:
	s_waitcnt vmcnt(11)
	v_bfe_u32 v34, v30, 16, 1
	v_add3_u32 v30, v30, v34, s86
	s_waitcnt vmcnt(10)
	v_bfe_u32 v34, v26, 16, 1
	v_lshrrev_b32_e32 v30, 16, v30
	v_add3_u32 v26, v26, v34, s86
	v_and_or_b32 v34, v26, s87, v30
	s_waitcnt vmcnt(9)
	v_bfe_u32 v26, v22, 16, 1
	v_add3_u32 v22, v22, v26, s86
	s_waitcnt vmcnt(8)
	v_bfe_u32 v26, v18, 16, 1
	v_lshrrev_b32_e32 v22, 16, v22
	v_add3_u32 v18, v18, v26, s86
	v_and_or_b32 v35, v18, s87, v22
	s_waitcnt vmcnt(7)
	v_bfe_u32 v18, v14, 16, 1
	v_add3_u32 v14, v14, v18, s86
	s_waitcnt vmcnt(6)
	v_bfe_u32 v18, v10, 16, 1
	v_lshrrev_b32_e32 v14, 16, v14
	v_add3_u32 v10, v10, v18, s86
	v_and_or_b32 v36, v10, s87, v14
	s_waitcnt vmcnt(5)
	v_bfe_u32 v10, v6, 16, 1
	v_add3_u32 v6, v6, v10, s86
	s_waitcnt vmcnt(4)
	v_bfe_u32 v10, v2, 16, 1
	v_add_u32_e32 v1, s44, v162
	v_lshrrev_b32_e32 v6, 16, v6
	v_add3_u32 v2, v2, v10, s86
	v_and_or_b32 v37, v2, s87, v6
	v_ashrrev_i32_e32 v2, 31, v1
	v_mul_lo_u32 v10, s38, v2
	v_mul_lo_u32 v2, s39, v1
	v_mad_u64_u32 v[38:39], s[10:11], s38, v1, 0
	v_add3_u32 v39, v39, v10, v2
	v_lshl_add_u64 v[38:39], v[38:39], 1, s[30:31]
	s_lshl_b64 s[10:11], s[40:41], 1
	v_bfe_u32 v2, v31, 16, 1
	v_lshl_add_u64 v[38:39], v[38:39], 0, s[10:11]
	v_add3_u32 v2, v31, v2, s86
	v_bfe_u32 v6, v27, 16, 1
	v_lshl_add_u64 v[38:39], v[38:39], 0, v[164:165]
	v_lshrrev_b32_e32 v2, 16, v2
	v_add3_u32 v6, v27, v6, s86
	global_store_dwordx4 v[38:39], v[34:37], off
	s_nop 1
	v_and_or_b32 v34, v6, s87, v2
	v_bfe_u32 v2, v23, 16, 1
	v_add3_u32 v2, v23, v2, s86
	v_bfe_u32 v6, v19, 16, 1
	v_lshrrev_b32_e32 v2, 16, v2
	v_add3_u32 v6, v19, v6, s86
	v_and_or_b32 v35, v6, s87, v2
	v_bfe_u32 v2, v15, 16, 1
	v_add3_u32 v2, v15, v2, s86
	v_bfe_u32 v6, v11, 16, 1
	v_lshrrev_b32_e32 v2, 16, v2
	v_add3_u32 v6, v11, v6, s86
	v_and_or_b32 v36, v6, s87, v2
	v_bfe_u32 v2, v7, 16, 1
	v_add3_u32 v2, v7, v2, s86
	v_bfe_u32 v6, v3, 16, 1
	v_lshrrev_b32_e32 v2, 16, v2
	v_add3_u32 v3, v3, v6, s86
	v_and_or_b32 v37, v3, s87, v2
	v_or_b32_e32 v2, 1, v1
	v_mul_lo_u32 v6, s39, v2
	v_mad_u64_u32 v[2:3], s[12:13], s38, v2, 0
	v_add3_u32 v3, v3, v10, v6
	v_lshl_add_u64 v[2:3], v[2:3], 1, s[30:31]
	v_lshl_add_u64 v[2:3], v[2:3], 0, s[10:11]
	v_lshl_add_u64 v[2:3], v[2:3], 0, v[164:165]
	global_store_dwordx4 v[2:3], v[34:37], off
	v_bfe_u32 v2, v32, 16, 1
	v_add3_u32 v2, v32, v2, s86
	v_bfe_u32 v3, v28, 16, 1
	v_lshrrev_b32_e32 v2, 16, v2
	v_add3_u32 v3, v28, v3, s86
	v_and_or_b32 v34, v3, s87, v2
	v_bfe_u32 v2, v24, 16, 1
	v_add3_u32 v2, v24, v2, s86
	v_bfe_u32 v3, v20, 16, 1
	v_lshrrev_b32_e32 v2, 16, v2
	v_add3_u32 v3, v20, v3, s86
	v_and_or_b32 v35, v3, s87, v2
	v_bfe_u32 v2, v16, 16, 1
	v_add3_u32 v2, v16, v2, s86
	v_bfe_u32 v3, v12, 16, 1
	v_lshrrev_b32_e32 v2, 16, v2
	v_add3_u32 v3, v12, v3, s86
	v_and_or_b32 v36, v3, s87, v2
	v_bfe_u32 v2, v8, 16, 1
	v_add3_u32 v2, v8, v2, s86
	v_bfe_u32 v3, v4, 16, 1
	v_lshrrev_b32_e32 v2, 16, v2
	v_add3_u32 v3, v4, v3, s86
	v_and_or_b32 v37, v3, s87, v2
	v_or_b32_e32 v2, 2, v1
	v_mul_lo_u32 v4, s39, v2
	v_mad_u64_u32 v[2:3], s[12:13], s38, v2, 0
	v_add3_u32 v3, v3, v10, v4
	v_lshl_add_u64 v[2:3], v[2:3], 1, s[30:31]
	v_lshl_add_u64 v[2:3], v[2:3], 0, s[10:11]
	v_lshl_add_u64 v[2:3], v[2:3], 0, v[164:165]
	global_store_dwordx4 v[2:3], v[34:37], off
	v_bfe_u32 v2, v33, 16, 1
	v_add3_u32 v2, v33, v2, s86
	v_bfe_u32 v3, v29, 16, 1
	v_lshrrev_b32_e32 v2, 16, v2
	v_add3_u32 v3, v29, v3, s86
	v_and_or_b32 v2, v3, s87, v2
	v_bfe_u32 v3, v25, 16, 1
	v_add3_u32 v3, v25, v3, s86
	v_bfe_u32 v4, v21, 16, 1
	v_lshrrev_b32_e32 v3, 16, v3
	v_add3_u32 v4, v21, v4, s86
	v_and_or_b32 v3, v4, s87, v3
	v_bfe_u32 v4, v17, 16, 1
	v_add3_u32 v4, v17, v4, s86
	v_bfe_u32 v6, v13, 16, 1
	v_lshrrev_b32_e32 v4, 16, v4
	v_add3_u32 v6, v13, v6, s86
	v_and_or_b32 v4, v6, s87, v4
	v_bfe_u32 v6, v9, 16, 1
	v_add3_u32 v6, v9, v6, s86
	v_bfe_u32 v7, v5, 16, 1
	v_lshrrev_b32_e32 v6, 16, v6
	v_add3_u32 v5, v5, v7, s86
	v_or_b32_e32 v1, 3, v1
	v_and_or_b32 v5, v5, s87, v6
	v_mul_lo_u32 v8, s39, v1
	v_mad_u64_u32 v[6:7], s[12:13], s38, v1, 0
	v_add3_u32 v7, v7, v10, v8
	v_lshl_add_u64 v[6:7], v[6:7], 1, s[30:31]
	v_lshl_add_u64 v[6:7], v[6:7], 0, s[10:11]
	v_lshl_add_u64 v[6:7], v[6:7], 0, v[164:165]
	global_store_dwordx4 v[6:7], v[2:5], off

; __device__ __forceinline__ unsigned f2bf(float f) { unsigned u = __builtin_bit_cast(unsigned, f); return (u + 0x7fffu + ((u >> 16) & 1u)) >> 16; }
; __device__ __forceinline__ unsigned pk2(float lo, float hi) { return f2bf(lo) | (f2bf(hi) << 16); }
; __device__ __forceinline__ void p0_store(const P0Item& q, int lane, f32x4 (&v)[8]) {
;     const int nblk = q.N / 32, kb = q.item / nblk, nb = q.item % nblk, k0 = 64 * kb, n0 = 32 * nb, c = lane & 7, n4 = lane >> 3;
;     if (q.gain) { const f32x4 g0 = *(const f32x4*)(q.gain + k0 + 8 * c), g1 = *(const f32x4*)(q.gain + k0 + 8 * c + 4);
;         v[0] = v[0] * g0.x; v[1] = v[1] * g0.y; v[2] = v[2] * g0.z; v[3] = v[3] * g0.w; v[4] = v[4] * g1.x; v[5] = v[5] * g1.y; v[6] = v[6] * g1.z; v[7] = v[7] * g1.w; }
; #pragma unroll
;     for (int e = 0; e < 4; ++e) { v4u o; o.x = pk2(v[0][e], v[1][e]); o.y = pk2(v[2][e], v[3][e]); o.z = pk2(v[4][e], v[5][e]); o.w = pk2(v[6][e], v[7][e]);
;         __builtin_nontemporal_store(o, (v4u*)(q.WT + (size_t)(n0 + 4 * n4 + e) * q.K + k0 + 8 * c)); }
.LBB0_100:
	s_waitcnt vmcnt(28)
	v_bfe_u32 v98, v134, 16, 1
	v_add3_u32 v98, v134, v98, s86
	v_bfe_u32 v99, v138, 16, 1
	v_lshrrev_b32_e32 v98, 16, v98
	v_add3_u32 v99, v138, v99, s86
	v_and_or_b32 v98, v99, s87, v98
	v_bfe_u32 v99, v142, 16, 1
	v_add3_u32 v99, v142, v99, s86
	v_bfe_u32 v100, v156, 16, 1
	v_lshrrev_b32_e32 v99, 16, v99
	v_add3_u32 v100, v156, v100, s86
	v_and_or_b32 v99, v100, s87, v99
	v_bfe_u32 v100, v146, 16, 1
	v_add3_u32 v100, v146, v100, s86
	v_bfe_u32 v101, v150, 16, 1
	v_lshrrev_b32_e32 v100, 16, v100
	v_add3_u32 v101, v150, v101, s86
	v_and_or_b32 v100, v101, s87, v100
	v_bfe_u32 v101, v154, 16, 1
	v_add3_u32 v101, v154, v101, s86
	v_bfe_u32 v102, v130, 16, 1
	v_add_u32_e32 v1, s64, v162
	v_lshrrev_b32_e32 v101, 16, v101
	v_add3_u32 v102, v130, v102, s86
	v_and_or_b32 v101, v102, s87, v101
	v_ashrrev_i32_e32 v102, 31, v1
	v_mul_lo_u32 v104, s12, v102
	v_mul_lo_u32 v105, s13, v1
	v_mad_u64_u32 v[102:103], s[34:35], s12, v1, 0
	v_add3_u32 v103, v103, v104, v105
	v_lshl_add_u64 v[102:103], v[102:103], 1, s[10:11]
	s_lshl_b64 s[34:35], s[60:61], 1
	v_lshl_add_u64 v[102:103], v[102:103], 0, s[34:35]
	v_lshlrev_b32_e32 v164, 1, v160
	v_lshl_add_u64 v[102:103], v[102:103], 0, v[164:165]
	global_store_dwordx4 v[102:103], v[98:101], off
	v_bfe_u32 v102, v131, 16, 1
	v_add3_u32 v102, v131, v102, s86
	v_bfe_u32 v98, v135, 16, 1
	v_add3_u32 v98, v135, v98, s86
	v_bfe_u32 v99, v139, 16, 1
	v_lshrrev_b32_e32 v98, 16, v98
	v_add3_u32 v99, v139, v99, s86
	v_and_or_b32 v98, v99, s87, v98
	v_bfe_u32 v99, v143, 16, 1
	v_add3_u32 v99, v143, v99, s86
	v_bfe_u32 v100, v157, 16, 1
	v_lshrrev_b32_e32 v99, 16, v99
	v_add3_u32 v100, v157, v100, s86
	v_and_or_b32 v99, v100, s87, v99
	v_bfe_u32 v100, v147, 16, 1
	v_add3_u32 v100, v147, v100, s86
	v_bfe_u32 v101, v151, 16, 1
	v_lshrrev_b32_e32 v100, 16, v100
	v_add3_u32 v101, v151, v101, s86
	v_and_or_b32 v100, v101, s87, v100
	v_bfe_u32 v101, v155, 16, 1
	v_add3_u32 v101, v155, v101, s86
	v_lshrrev_b32_e32 v101, 16, v101
	v_and_or_b32 v101, v102, s87, v101
	v_or_b32_e32 v102, 1, v1
	v_mul_lo_u32 v105, s13, v102
	v_mad_u64_u32 v[102:103], s[52:53], s12, v102, 0
	v_add3_u32 v103, v103, v104, v105
	v_lshl_add_u64 v[102:103], v[102:103], 1, s[10:11]
	v_lshl_add_u64 v[102:103], v[102:103], 0, s[34:35]
	v_lshl_add_u64 v[102:103], v[102:103], 0, v[164:165]
	global_store_dwordx4 v[102:103], v[98:101], off
	v_bfe_u32 v102, v132, 16, 1
	v_add3_u32 v102, v132, v102, s86
	v_bfe_u32 v98, v136, 16, 1
	v_add3_u32 v98, v136, v98, s86
	v_bfe_u32 v99, v140, 16, 1
	v_lshrrev_b32_e32 v98, 16, v98
	v_add3_u32 v99, v140, v99, s86
	v_and_or_b32 v98, v99, s87, v98
	v_bfe_u32 v99, v144, 16, 1
	v_add3_u32 v99, v144, v99, s86
	v_bfe_u32 v100, v168, 16, 1
	v_lshrrev_b32_e32 v99, 16, v99
	v_add3_u32 v100, v168, v100, s86
	v_and_or_b32 v99, v100, s87, v99
	v_bfe_u32 v100, v148, 16, 1
	v_add3_u32 v100, v148, v100, s86
	v_bfe_u32 v101, v152, 16, 1
	v_lshrrev_b32_e32 v100, 16, v100
	v_add3_u32 v101, v152, v101, s86
	v_and_or_b32 v100, v101, s87, v100
	v_bfe_u32 v101, v158, 16, 1
	v_add3_u32 v101, v158, v101, s86
	v_lshrrev_b32_e32 v101, 16, v101
	v_and_or_b32 v101, v102, s87, v101
	v_or_b32_e32 v102, 2, v1
	v_mul_lo_u32 v105, s13, v102
	v_mad_u64_u32 v[102:103], s[52:53], s12, v102, 0
	v_add3_u32 v103, v103, v104, v105
	v_lshl_add_u64 v[102:103], v[102:103], 1, s[10:11]
	v_lshl_add_u64 v[102:103], v[102:103], 0, s[34:35]
	v_lshl_add_u64 v[102:103], v[102:103], 0, v[164:165]
	global_store_dwordx4 v[102:103], v[98:101], off
	v_bfe_u32 v102, v133, 16, 1
	v_add3_u32 v102, v133, v102, s86
	v_bfe_u32 v98, v137, 16, 1
	v_add3_u32 v98, v137, v98, s86
	v_bfe_u32 v99, v141, 16, 1
	v_lshrrev_b32_e32 v98, 16, v98
	v_add3_u32 v99, v141, v99, s86
	v_and_or_b32 v98, v99, s87, v98
	v_bfe_u32 v99, v145, 16, 1
	v_add3_u32 v99, v145, v99, s86
	v_bfe_u32 v100, v169, 16, 1
	v_lshrrev_b32_e32 v99, 16, v99
	v_add3_u32 v100, v169, v100, s86
	v_and_or_b32 v99, v100, s87, v99
	v_bfe_u32 v100, v149, 16, 1
	v_add3_u32 v100, v149, v100, s86
	v_bfe_u32 v101, v153, 16, 1
	v_lshrrev_b32_e32 v100, 16, v100
	v_add3_u32 v101, v153, v101, s86
	v_and_or_b32 v100, v101, s87, v100
	v_bfe_u32 v101, v159, 16, 1
	v_add3_u32 v101, v159, v101, s86
	v_lshrrev_b32_e32 v101, 16, v101
	v_or_b32_e32 v1, 3, v1
	v_and_or_b32 v101, v102, s87, v101
	v_mul_lo_u32 v105, s13, v1
	v_mad_u64_u32 v[102:103], s[12:13], s12, v1, 0
	v_add3_u32 v103, v103, v104, v105
	v_lshl_add_u64 v[102:103], v[102:103], 1, s[10:11]
	v_lshl_add_u64 v[102:103], v[102:103], 0, s[34:35]
	v_lshl_add_u64 v[102:103], v[102:103], 0, v[164:165]
	s_andn2_b64 vcc, exec, s[16:17]
	global_store_dwordx4 v[102:103], v[98:101], off
	s_cbranch_vccz .LBB0_103
	s_andn2_b64 vcc, exec, s[24:25]
	s_cbranch_vccz .LBB0_106

; __device__ __forceinline__ unsigned f2bf(float f) { unsigned u = __builtin_bit_cast(unsigned, f); return (u + 0x7fffu + ((u >> 16) & 1u)) >> 16; }
; __device__ __forceinline__ unsigned pk2(float lo, float hi) { return f2bf(lo) | (f2bf(hi) << 16); }
; __device__ __forceinline__ void p0_store(const P0Item& q, int lane, f32x4 (&v)[8]) {
;     const int nblk = q.N / 32, kb = q.item / nblk, nb = q.item % nblk, k0 = 64 * kb, n0 = 32 * nb, c = lane & 7, n4 = lane >> 3;
;     if (q.gain) { const f32x4 g0 = *(const f32x4*)(q.gain + k0 + 8 * c), g1 = *(const f32x4*)(q.gain + k0 + 8 * c + 4);
;         v[0] = v[0] * g0.x; v[1] = v[1] * g0.y; v[2] = v[2] * g0.z; v[3] = v[3] * g0.w; v[4] = v[4] * g1.x; v[5] = v[5] * g1.y; v[6] = v[6] * g1.z; v[7] = v[7] * g1.w; }
; #pragma unroll
;     for (int e = 0; e < 4; ++e) { v4u o; o.x = pk2(v[0][e], v[1][e]); o.y = pk2(v[2][e], v[3][e]); o.z = pk2(v[4][e], v[5][e]); o.w = pk2(v[6][e], v[7][e]);
;         __builtin_nontemporal_store(o, (v4u*)(q.WT + (size_t)(n0 + 4 * n4 + e) * q.K + k0 + 8 * c)); }
.LBB0_105:
	s_waitcnt vmcnt(27)
	v_bfe_u32 v98, v78, 16, 1
	v_add3_u32 v78, v78, v98, s86
	s_waitcnt vmcnt(26)
	v_bfe_u32 v98, v70, 16, 1
	v_lshrrev_b32_e32 v78, 16, v78
	v_add3_u32 v70, v70, v98, s86
	v_and_or_b32 v98, v70, s87, v78
	s_waitcnt vmcnt(25)
	v_bfe_u32 v70, v74, 16, 1
	v_add3_u32 v70, v74, v70, s86
	s_waitcnt vmcnt(24)
	v_bfe_u32 v74, v66, 16, 1
	v_lshrrev_b32_e32 v70, 16, v70
	v_add3_u32 v66, v66, v74, s86
	v_and_or_b32 v99, v66, s87, v70
	s_waitcnt vmcnt(23)
	v_bfe_u32 v66, v94, 16, 1
	v_add3_u32 v66, v94, v66, s86
	s_waitcnt vmcnt(22)
	v_bfe_u32 v70, v90, 16, 1
	v_lshrrev_b32_e32 v66, 16, v66
	v_add3_u32 v70, v90, v70, s86
	v_and_or_b32 v100, v70, s87, v66
	s_waitcnt vmcnt(21)
	v_bfe_u32 v66, v86, 16, 1
	v_add3_u32 v66, v86, v66, s86
	s_waitcnt vmcnt(20)
	v_bfe_u32 v70, v82, 16, 1
	v_add_u32_e32 v1, s58, v162
	v_lshrrev_b32_e32 v66, 16, v66
	v_add3_u32 v70, v82, v70, s86
	v_and_or_b32 v101, v70, s87, v66
	v_ashrrev_i32_e32 v66, 31, v1
	v_mul_lo_u32 v74, s18, v66
	v_mul_lo_u32 v66, s19, v1
	v_mad_u64_u32 v[102:103], s[10:11], s18, v1, 0
	v_add3_u32 v103, v103, v74, v66
	v_lshl_add_u64 v[102:103], v[102:103], 1, s[14:15]
	s_lshl_b64 s[10:11], s[56:57], 1
	v_bfe_u32 v66, v79, 16, 1
	v_lshl_add_u64 v[102:103], v[102:103], 0, s[10:11]
	v_add3_u32 v66, v79, v66, s86
	v_bfe_u32 v70, v71, 16, 1
	v_lshl_add_u64 v[102:103], v[102:103], 0, v[164:165]
	v_lshrrev_b32_e32 v66, 16, v66
	v_add3_u32 v70, v71, v70, s86
	global_store_dwordx4 v[102:103], v[98:101], off
	s_nop 1
	v_and_or_b32 v98, v70, s87, v66
	v_bfe_u32 v66, v75, 16, 1
	v_add3_u32 v66, v75, v66, s86
	v_bfe_u32 v70, v67, 16, 1
	v_lshrrev_b32_e32 v66, 16, v66
	v_add3_u32 v67, v67, v70, s86
	v_and_or_b32 v99, v67, s87, v66
	v_bfe_u32 v66, v95, 16, 1
	v_add3_u32 v66, v95, v66, s86
	v_bfe_u32 v67, v91, 16, 1
	v_lshrrev_b32_e32 v66, 16, v66
	v_add3_u32 v67, v91, v67, s86
	v_and_or_b32 v100, v67, s87, v66
	v_bfe_u32 v66, v87, 16, 1
	v_add3_u32 v66, v87, v66, s86
	v_bfe_u32 v67, v83, 16, 1
	v_lshrrev_b32_e32 v66, 16, v66
	v_add3_u32 v67, v83, v67, s86
	v_and_or_b32 v101, v67, s87, v66
	v_or_b32_e32 v66, 1, v1
	v_mul_lo_u32 v70, s19, v66
	v_mad_u64_u32 v[66:67], s[12:13], s18, v66, 0
	v_add3_u32 v67, v67, v74, v70
	v_lshl_add_u64 v[66:67], v[66:67], 1, s[14:15]
	v_lshl_add_u64 v[66:67], v[66:67], 0, s[10:11]
	v_lshl_add_u64 v[66:67], v[66:67], 0, v[164:165]
	global_store_dwordx4 v[66:67], v[98:101], off
	v_bfe_u32 v66, v80, 16, 1
	v_add3_u32 v66, v80, v66, s86
	v_bfe_u32 v67, v72, 16, 1
	v_lshrrev_b32_e32 v66, 16, v66
	v_add3_u32 v67, v72, v67, s86
	v_and_or_b32 v98, v67, s87, v66
	v_bfe_u32 v66, v76, 16, 1
	v_add3_u32 v66, v76, v66, s86
	v_bfe_u32 v67, v68, 16, 1
	v_lshrrev_b32_e32 v66, 16, v66
	v_add3_u32 v67, v68, v67, s86
	v_and_or_b32 v99, v67, s87, v66
	v_bfe_u32 v66, v96, 16, 1
	v_add3_u32 v66, v96, v66, s86
	v_bfe_u32 v67, v92, 16, 1
	v_lshrrev_b32_e32 v66, 16, v66
	v_add3_u32 v67, v92, v67, s86
	v_and_or_b32 v100, v67, s87, v66
	v_bfe_u32 v66, v88, 16, 1
	v_add3_u32 v66, v88, v66, s86
	v_bfe_u32 v67, v84, 16, 1
	v_lshrrev_b32_e32 v66, 16, v66
	v_add3_u32 v67, v84, v67, s86
	v_and_or_b32 v101, v67, s87, v66
	v_or_b32_e32 v66, 2, v1
	v_mul_lo_u32 v68, s19, v66
	v_mad_u64_u32 v[66:67], s[12:13], s18, v66, 0
	v_add3_u32 v67, v67, v74, v68
	v_lshl_add_u64 v[66:67], v[66:67], 1, s[14:15]
	v_lshl_add_u64 v[66:67], v[66:67], 0, s[10:11]
	v_lshl_add_u64 v[66:67], v[66:67], 0, v[164:165]
	global_store_dwordx4 v[66:67], v[98:101], off
	v_bfe_u32 v66, v81, 16, 1
	v_add3_u32 v66, v81, v66, s86
	v_bfe_u32 v67, v73, 16, 1
	v_lshrrev_b32_e32 v66, 16, v66
	v_add3_u32 v67, v73, v67, s86
	v_and_or_b32 v66, v67, s87, v66
	v_bfe_u32 v67, v77, 16, 1
	v_add3_u32 v67, v77, v67, s86
	v_bfe_u32 v68, v69, 16, 1
	v_lshrrev_b32_e32 v67, 16, v67
	v_add3_u32 v68, v69, v68, s86
	v_and_or_b32 v67, v68, s87, v67
	v_bfe_u32 v68, v97, 16, 1
	v_add3_u32 v68, v97, v68, s86
	v_bfe_u32 v69, v93, 16, 1
	v_lshrrev_b32_e32 v68, 16, v68
	v_add3_u32 v69, v93, v69, s86
	v_and_or_b32 v68, v69, s87, v68
	v_bfe_u32 v69, v89, 16, 1
	v_add3_u32 v69, v89, v69, s86
	v_bfe_u32 v70, v85, 16, 1
	v_lshrrev_b32_e32 v69, 16, v69
	v_add3_u32 v70, v85, v70, s86
	v_or_b32_e32 v1, 3, v1
	v_and_or_b32 v69, v70, s87, v69
	v_mul_lo_u32 v72, s19, v1
	v_mad_u64_u32 v[70:71], s[12:13], s18, v1, 0
	v_add3_u32 v71, v71, v74, v72
	v_lshl_add_u64 v[70:71], v[70:71], 1, s[14:15]
	v_lshl_add_u64 v[70:71], v[70:71], 0, s[10:11]
	v_lshl_add_u64 v[70:71], v[70:71], 0, v[164:165]
	global_store_dwordx4 v[70:71], v[66:69], off
	s_andn2_b64 vcc, exec, s[24:25]
	s_cbranch_vccnz .LBB0_102

; __device__ __forceinline__ unsigned f2bf(float f) { unsigned u = __builtin_bit_cast(unsigned, f); return (u + 0x7fffu + ((u >> 16) & 1u)) >> 16; }
; __device__ __forceinline__ unsigned pk2(float lo, float hi) { return f2bf(lo) | (f2bf(hi) << 16); }
; __device__ __forceinline__ void p0_store(const P0Item& q, int lane, f32x4 (&v)[8]) {
;     const int nblk = q.N / 32, kb = q.item / nblk, nb = q.item % nblk, k0 = 64 * kb, n0 = 32 * nb, c = lane & 7, n4 = lane >> 3;
;     if (q.gain) { const f32x4 g0 = *(const f32x4*)(q.gain + k0 + 8 * c), g1 = *(const f32x4*)(q.gain + k0 + 8 * c + 4);
;         v[0] = v[0] * g0.x; v[1] = v[1] * g0.y; v[2] = v[2] * g0.z; v[3] = v[3] * g0.w; v[4] = v[4] * g1.x; v[5] = v[5] * g1.y; v[6] = v[6] * g1.z; v[7] = v[7] * g1.w; }
; #pragma unroll
;     for (int e = 0; e < 4; ++e) { v4u o; o.x = pk2(v[0][e], v[1][e]); o.y = pk2(v[2][e], v[3][e]); o.z = pk2(v[4][e], v[5][e]); o.w = pk2(v[6][e], v[7][e]);
;         __builtin_nontemporal_store(o, (v4u*)(q.WT + (size_t)(n0 + 4 * n4 + e) * q.K + k0 + 8 * c)); }
.LBB0_108:
	s_waitcnt vmcnt(19)
	v_bfe_u32 v66, v62, 16, 1
	v_add3_u32 v62, v62, v66, s86
	s_waitcnt vmcnt(18)
	v_bfe_u32 v66, v58, 16, 1
	v_lshrrev_b32_e32 v62, 16, v62
	v_add3_u32 v58, v58, v66, s86
	v_and_or_b32 v66, v58, s87, v62
	s_waitcnt vmcnt(17)
	v_bfe_u32 v58, v54, 16, 1
	v_add3_u32 v54, v54, v58, s86
	s_waitcnt vmcnt(16)
	v_bfe_u32 v58, v50, 16, 1
	v_lshrrev_b32_e32 v54, 16, v54
	v_add3_u32 v50, v50, v58, s86
	v_and_or_b32 v67, v50, s87, v54
	s_waitcnt vmcnt(15)
	v_bfe_u32 v50, v46, 16, 1
	v_add3_u32 v46, v46, v50, s86
	s_waitcnt vmcnt(14)
	v_bfe_u32 v50, v42, 16, 1
	v_lshrrev_b32_e32 v46, 16, v46
	v_add3_u32 v42, v42, v50, s86
	v_and_or_b32 v68, v42, s87, v46
	s_waitcnt vmcnt(13)
	v_bfe_u32 v42, v38, 16, 1
	v_add3_u32 v38, v38, v42, s86
	s_waitcnt vmcnt(12)
	v_bfe_u32 v42, v34, 16, 1
	v_add_u32_e32 v1, s50, v162
	v_lshrrev_b32_e32 v38, 16, v38
	v_add3_u32 v34, v34, v42, s86
	v_and_or_b32 v69, v34, s87, v38
	v_ashrrev_i32_e32 v34, 31, v1
	v_mul_lo_u32 v42, s26, v34
	v_mul_lo_u32 v34, s27, v1
	v_mad_u64_u32 v[70:71], s[10:11], s26, v1, 0
	v_add3_u32 v71, v71, v42, v34
	v_lshl_add_u64 v[70:71], v[70:71], 1, s[20:21]
	s_lshl_b64 s[10:11], s[48:49], 1
	v_bfe_u32 v34, v63, 16, 1
	v_lshl_add_u64 v[70:71], v[70:71], 0, s[10:11]
	v_add3_u32 v34, v63, v34, s86
	v_bfe_u32 v38, v59, 16, 1
	v_lshl_add_u64 v[70:71], v[70:71], 0, v[164:165]
	v_lshrrev_b32_e32 v34, 16, v34
	v_add3_u32 v38, v59, v38, s86
	global_store_dwordx4 v[70:71], v[66:69], off
	s_nop 1
	v_and_or_b32 v66, v38, s87, v34
	v_bfe_u32 v34, v55, 16, 1
	v_add3_u32 v34, v55, v34, s86
	v_bfe_u32 v38, v51, 16, 1
	v_lshrrev_b32_e32 v34, 16, v34
	v_add3_u32 v38, v51, v38, s86
	v_and_or_b32 v67, v38, s87, v34
	v_bfe_u32 v34, v47, 16, 1
	v_add3_u32 v34, v47, v34, s86
	v_bfe_u32 v38, v43, 16, 1
	v_lshrrev_b32_e32 v34, 16, v34
	v_add3_u32 v38, v43, v38, s86
	v_and_or_b32 v68, v38, s87, v34
	v_bfe_u32 v34, v39, 16, 1
	v_add3_u32 v34, v39, v34, s86
	v_bfe_u32 v38, v35, 16, 1
	v_lshrrev_b32_e32 v34, 16, v34
	v_add3_u32 v35, v35, v38, s86
	v_and_or_b32 v69, v35, s87, v34
	v_or_b32_e32 v34, 1, v1
	v_mul_lo_u32 v38, s27, v34
	v_mad_u64_u32 v[34:35], s[12:13], s26, v34, 0
	v_add3_u32 v35, v35, v42, v38
	v_lshl_add_u64 v[34:35], v[34:35], 1, s[20:21]
	v_lshl_add_u64 v[34:35], v[34:35], 0, s[10:11]
	v_lshl_add_u64 v[34:35], v[34:35], 0, v[164:165]
	global_store_dwordx4 v[34:35], v[66:69], off
	v_bfe_u32 v34, v64, 16, 1
	v_add3_u32 v34, v64, v34, s86
	v_bfe_u32 v35, v60, 16, 1
	v_lshrrev_b32_e32 v34, 16, v34
	v_add3_u32 v35, v60, v35, s86
	v_and_or_b32 v66, v35, s87, v34
	v_bfe_u32 v34, v56, 16, 1
	v_add3_u32 v34, v56, v34, s86
	v_bfe_u32 v35, v52, 16, 1
	v_lshrrev_b32_e32 v34, 16, v34
	v_add3_u32 v35, v52, v35, s86
	v_and_or_b32 v67, v35, s87, v34
	v_bfe_u32 v34, v48, 16, 1
	v_add3_u32 v34, v48, v34, s86
	v_bfe_u32 v35, v44, 16, 1
	v_lshrrev_b32_e32 v34, 16, v34
	v_add3_u32 v35, v44, v35, s86
	v_and_or_b32 v68, v35, s87, v34
	v_bfe_u32 v34, v40, 16, 1
	v_add3_u32 v34, v40, v34, s86
	v_bfe_u32 v35, v36, 16, 1
	v_lshrrev_b32_e32 v34, 16, v34
	v_add3_u32 v35, v36, v35, s86
	v_and_or_b32 v69, v35, s87, v34
	v_or_b32_e32 v34, 2, v1
	v_mul_lo_u32 v36, s27, v34
	v_mad_u64_u32 v[34:35], s[12:13], s26, v34, 0
	v_add3_u32 v35, v35, v42, v36
	v_lshl_add_u64 v[34:35], v[34:35], 1, s[20:21]
	v_lshl_add_u64 v[34:35], v[34:35], 0, s[10:11]
	v_lshl_add_u64 v[34:35], v[34:35], 0, v[164:165]
	global_store_dwordx4 v[34:35], v[66:69], off
	v_bfe_u32 v34, v65, 16, 1
	v_add3_u32 v34, v65, v34, s86
	v_bfe_u32 v35, v61, 16, 1
	v_lshrrev_b32_e32 v34, 16, v34
	v_add3_u32 v35, v61, v35, s86
	v_and_or_b32 v34, v35, s87, v34
	v_bfe_u32 v35, v57, 16, 1
	v_add3_u32 v35, v57, v35, s86
	v_bfe_u32 v36, v53, 16, 1
	v_lshrrev_b32_e32 v35, 16, v35
	v_add3_u32 v36, v53, v36, s86
	v_and_or_b32 v35, v36, s87, v35
	v_bfe_u32 v36, v49, 16, 1
	v_add3_u32 v36, v49, v36, s86
	v_bfe_u32 v38, v45, 16, 1
	v_lshrrev_b32_e32 v36, 16, v36
	v_add3_u32 v38, v45, v38, s86
	v_and_or_b32 v36, v38, s87, v36
	v_bfe_u32 v38, v41, 16, 1
	v_add3_u32 v38, v41, v38, s86
	v_bfe_u32 v39, v37, 16, 1
	v_lshrrev_b32_e32 v38, 16, v38
	v_add3_u32 v37, v37, v39, s86
	v_or_b32_e32 v1, 3, v1
	v_and_or_b32 v37, v37, s87, v38
	v_mul_lo_u32 v40, s27, v1
	v_mad_u64_u32 v[38:39], s[12:13], s26, v1, 0
	v_add3_u32 v39, v39, v42, v40
	v_lshl_add_u64 v[38:39], v[38:39], 1, s[20:21]
	v_lshl_add_u64 v[38:39], v[38:39], 0, s[10:11]
	v_lshl_add_u64 v[38:39], v[38:39], 0, v[164:165]
	global_store_dwordx4 v[38:39], v[34:37], off
	s_andn2_b64 vcc, exec, s[36:37]
	s_cbranch_vccnz .LBB0_24
